# strategy lever 1 on GEMM epilogues: merge-GEMM gate loads waited per 16-row group (vmcnt 7..0), mix-out epilogue's batch-start drains moved onto the skip edge
# speedup vs baseline: 1.0081x; 1.0038x over previous
; __device__ __forceinline__ unsigned cvt_pk_bf16(float lo, float hi) { return pk2(lo, hi); }
; __device__ __forceinline__ f32x4 bf4lo(u32x4 g) { return (f32x4){__builtin_bit_cast(float, g.x << 16), __builtin_bit_cast(float, g.x & 0xffff0000u), __builtin_bit_cast(float, g.y << 16), __builtin_bit_cast(float, g.y & 0xffff0000u)}; }
; __device__ __forceinline__ f32x4 bf4hi(u32x4 g) { return (f32x4){__builtin_bit_cast(float, g.z << 16), __builtin_bit_cast(float, g.z & 0xffff0000u), __builtin_bit_cast(float, g.w << 16), __builtin_bit_cast(float, g.w & 0xffff0000u)}; }
;     __device__ __forceinline__ void operator()(const f32x4 (&acc)[2][1][4][2], f32x4 (&mr)[2][4][2], const Unit& u, int wr, int wc, int fr, int fq) const {
;         const int row0 = u.pm * BM + wr * 64 + fr, col0 = u.pn * HALF + wc * 32 + 8 * fq;
;         u32x4 gv[2][4];
; #pragma unroll
;         for (int ai = 0; ai < 2; ++ai)
; #pragma unroll
;             for (int m = 0; m < 4; ++m) gv[ai][m] = *(const u32x4*)(G + (size_t)(row0 + ai * HALF + m * 16) * NGATE + (size_t)u.pb * D + col0);
; #pragma unroll
;         for (int ai = 0; ai < 2; ++ai)
; #pragma unroll
;             for (int m = 0; m < 4; ++m) {
;                 const f32x4 p0 = acc[ai][0][m][0] * bf4lo(gv[ai][m]), p1 = acc[ai][0][m][1] * bf4hi(gv[ai][m]);
;                 if (u.pb == 0) { mr[ai][m][0] = p0; mr[ai][m][1] = p1; } else { mr[ai][m][0] += p0; mr[ai][m][1] += p1; }
;                 if (u.pb == 3) { const f32x4 v0 = mr[ai][m][0], v1 = mr[ai][m][1];
;                     u32x4 w; w.x = cvt_pk_bf16(v0[0], v0[1]); w.y = cvt_pk_bf16(v0[2], v0[3]); w.z = cvt_pk_bf16(v1[0], v1[1]); w.w = cvt_pk_bf16(v1[2], v1[3]);
;                     *(u32x4*)(MB + (size_t)(row0 + ai * HALF + m * 16) * D + col0) = w; } }
.LBB0_1375:
	v_lshl_or_b32 v182, s43, 7, v203
	s_ashr_i32 s43, s42, 31
	v_lshl_add_u32 v198, s48, 8, v200
	s_lshl_b64 s[4:5], s[42:43], 12
	s_add_u32 s4, s10, s4
	v_or_b32_e32 v196, 16, v198
	s_addc_u32 s5, s11, s5
	v_ashrrev_i32_e32 v183, 31, v182
	v_ashrrev_i32_e32 v199, 31, v198
	v_ashrrev_i32_e32 v197, 31, v196
	v_lshl_add_u64 v[18:19], v[182:183], 1, s[4:5]
	v_lshlrev_b64 v[20:21], 14, v[198:199]
	v_lshlrev_b64 v[30:31], 14, v[196:197]
	v_or_b32_e32 v194, 32, v198
	v_or_b32_e32 v192, 48, v198
	v_lshl_add_u64 v[20:21], v[18:19], 0, v[20:21]
	v_lshl_add_u64 v[30:31], v[18:19], 0, v[30:31]
	v_ashrrev_i32_e32 v195, 31, v194
	v_ashrrev_i32_e32 v193, 31, v192
	global_load_dwordx4 v[204:207], v[20:21], off
	global_load_dwordx4 v[92:95], v[30:31], off
	v_lshlrev_b64 v[20:21], 14, v[194:195]
	v_lshlrev_b64 v[30:31], 14, v[192:193]
	v_add_u32_e32 v190, 0x80, v198
	v_add_u32_e32 v188, 0x90, v198
	v_lshl_add_u64 v[20:21], v[18:19], 0, v[20:21]
	v_lshl_add_u64 v[30:31], v[18:19], 0, v[30:31]
	v_ashrrev_i32_e32 v191, 31, v190
	v_ashrrev_i32_e32 v189, 31, v188
	global_load_dwordx4 v[80:83], v[20:21], off
	global_load_dwordx4 v[72:75], v[30:31], off
	v_lshlrev_b64 v[20:21], 14, v[190:191]
	v_lshlrev_b64 v[30:31], 14, v[188:189]
	v_add_u32_e32 v186, 0xa0, v198
	v_add_u32_e32 v184, 0xb0, v198
	v_lshl_add_u64 v[20:21], v[18:19], 0, v[20:21]
	v_lshl_add_u64 v[30:31], v[18:19], 0, v[30:31]
	v_ashrrev_i32_e32 v187, 31, v186
	v_ashrrev_i32_e32 v185, 31, v184
	global_load_dwordx4 v[64:67], v[20:21], off
	global_load_dwordx4 v[52:55], v[30:31], off
	v_lshlrev_b64 v[20:21], 14, v[186:187]
	v_lshlrev_b64 v[30:31], 14, v[184:185]
	v_lshl_add_u64 v[20:21], v[18:19], 0, v[20:21]
	v_lshl_add_u64 v[18:19], v[18:19], 0, v[30:31]
	global_load_dwordx4 v[30:33], v[20:21], off
	s_nop 0
	global_load_dwordx4 v[18:21], v[18:19], off
	s_cmp_eq_u32 s42, 0
	s_cselect_b64 s[38:39], -1, 0
	s_cmp_eq_u32 s42, 3
	s_cselect_b64 s[4:5], -1, 0
	s_cmp_lg_u32 s42, 3
	s_waitcnt vmcnt(7)
	v_lshlrev_b32_e32 v164, 16, v204
	v_and_b32_e32 v165, 0xffff0000, v204
	v_lshlrev_b32_e32 v166, 16, v205
	v_and_b32_e32 v167, 0xffff0000, v205
	v_lshlrev_b32_e32 v168, 16, v206
	v_and_b32_e32 v169, 0xffff0000, v206
	v_lshlrev_b32_e32 v204, 16, v207
	v_and_b32_e32 v205, 0xffff0000, v207
	v_pk_mul_f32 v[206:207], v[84:85], v[164:165]
	v_pk_mul_f32 v[222:223], v[86:87], v[166:167]
	v_pk_mul_f32 v[224:225], v[88:89], v[168:169]
	v_pk_mul_f32 v[226:227], v[90:91], v[204:205]
	v_pk_fma_f32 v[90:91], v[90:91], v[204:205], v[180:181]
	v_pk_fma_f32 v[84:85], v[84:85], v[164:165], v[162:163]
	v_pk_fma_f32 v[86:87], v[86:87], v[166:167], v[160:161]
	v_pk_fma_f32 v[88:89], v[88:89], v[168:169], v[158:159]
	v_cndmask_b32_e64 v181, v91, v227, s[38:39]
	v_cndmask_b32_e64 v180, v90, v226, s[38:39]
	v_cndmask_b32_e64 v159, v89, v225, s[38:39]
	v_cndmask_b32_e64 v158, v88, v224, s[38:39]
	v_cndmask_b32_e64 v161, v87, v223, s[38:39]
	v_cndmask_b32_e64 v160, v86, v222, s[38:39]
	v_cndmask_b32_e64 v163, v85, v207, s[38:39]
	v_cndmask_b32_e64 v162, v84, v206, s[38:39]
	s_cbranch_scc1 .LBB0_1377
	v_lshlrev_b64 v[88:89], 12, v[198:199]
	v_lshl_add_u64 v[88:89], s[8:9], 0, v[88:89]
	v_cvt_pk_bf16_f32 v84, v162, v163
	v_cvt_pk_bf16_f32 v85, v160, v161
	v_cvt_pk_bf16_f32 v86, v158, v159
	v_cvt_pk_bf16_f32 v87, v180, v181
	v_lshl_add_u64 v[88:89], v[182:183], 1, v[88:89]
	global_store_dwordx4 v[88:89], v[84:87], off
.LBB0_1377:
	s_waitcnt vmcnt(6)
	s_nop 1
	v_lshlrev_b32_e32 v84, 16, v92
	v_and_b32_e32 v85, 0xffff0000, v92
	v_lshlrev_b32_e32 v86, 16, v93
	v_and_b32_e32 v87, 0xffff0000, v93
	v_lshlrev_b32_e32 v92, 16, v94
	v_and_b32_e32 v93, 0xffff0000, v94
	v_lshlrev_b32_e32 v94, 16, v95
	v_and_b32_e32 v95, 0xffff0000, v95
	v_pk_mul_f32 v[164:165], v[68:69], v[92:93]
	v_pk_fma_f32 v[68:69], v[68:69], v[92:93], v[148:149]
	v_pk_mul_f32 v[88:89], v[76:77], v[84:85]
	v_pk_mul_f32 v[90:91], v[78:79], v[86:87]
	v_pk_mul_f32 v[166:167], v[70:71], v[94:95]
	v_pk_fma_f32 v[76:77], v[76:77], v[84:85], v[156:157]
	v_pk_fma_f32 v[78:79], v[78:79], v[86:87], v[154:155]
	v_pk_fma_f32 v[70:71], v[70:71], v[94:95], v[144:145]
	v_cndmask_b32_e64 v148, v68, v164, s[38:39]
	v_cndmask_b32_e64 v68, 0, 1, s[4:5]
	v_cndmask_b32_e64 v145, v71, v167, s[38:39]
	v_cndmask_b32_e64 v144, v70, v166, s[38:39]
	v_cndmask_b32_e64 v149, v69, v165, s[38:39]
	v_cndmask_b32_e64 v155, v79, v91, s[38:39]
	v_cndmask_b32_e64 v154, v78, v90, s[38:39]
	v_cndmask_b32_e64 v157, v77, v89, s[38:39]
	v_cmp_ne_u32_e64 s[42:43], 1, v68
	s_andn2_b64 vcc, exec, s[4:5]
	v_cndmask_b32_e64 v156, v76, v88, s[38:39]
	s_cbranch_vccnz .LBB0_1379
	v_lshlrev_b64 v[76:77], 12, v[196:197]
	v_lshl_add_u64 v[76:77], s[8:9], 0, v[76:77]
	v_cvt_pk_bf16_f32 v68, v156, v157
	v_cvt_pk_bf16_f32 v69, v154, v155
	v_cvt_pk_bf16_f32 v70, v148, v149
	v_cvt_pk_bf16_f32 v71, v144, v145
	v_lshl_add_u64 v[76:77], v[182:183], 1, v[76:77]
	global_store_dwordx4 v[76:77], v[68:71], off
.LBB0_1379:
	s_waitcnt vmcnt(5)
	s_nop 1
	v_lshlrev_b32_e32 v68, 16, v80
	v_and_b32_e32 v69, 0xffff0000, v80
	v_lshlrev_b32_e32 v70, 16, v81
	v_and_b32_e32 v71, 0xffff0000, v81
	v_lshlrev_b32_e32 v80, 16, v82
	v_and_b32_e32 v81, 0xffff0000, v82
	v_lshlrev_b32_e32 v82, 16, v83
	v_and_b32_e32 v83, 0xffff0000, v83
	v_pk_mul_f32 v[76:77], v[60:61], v[68:69]
	v_pk_mul_f32 v[78:79], v[62:63], v[70:71]
	v_pk_mul_f32 v[84:85], v[56:57], v[80:81]
	v_pk_mul_f32 v[86:87], v[58:59], v[82:83]
	v_pk_fma_f32 v[60:61], v[60:61], v[68:69], v[152:153]
	v_pk_fma_f32 v[62:63], v[62:63], v[70:71], v[150:151]
	v_pk_fma_f32 v[56:57], v[56:57], v[80:81], v[140:141]
	v_pk_fma_f32 v[58:59], v[58:59], v[82:83], v[136:137]
	v_cndmask_b32_e64 v141, v57, v85, s[38:39]
	v_cndmask_b32_e64 v137, v59, v87, s[38:39]
	v_cndmask_b32_e64 v136, v58, v86, s[38:39]
	v_cndmask_b32_e64 v140, v56, v84, s[38:39]
	v_cndmask_b32_e64 v151, v63, v79, s[38:39]
	v_cndmask_b32_e64 v150, v62, v78, s[38:39]
	v_cndmask_b32_e64 v153, v61, v77, s[38:39]
	s_and_b64 vcc, exec, s[42:43]
	v_cndmask_b32_e64 v152, v60, v76, s[38:39]
	s_cbranch_vccnz .LBB0_1381
	v_lshlrev_b64 v[60:61], 12, v[194:195]
	v_lshl_add_u64 v[60:61], s[8:9], 0, v[60:61]
	v_cvt_pk_bf16_f32 v56, v152, v153
	v_cvt_pk_bf16_f32 v57, v150, v151
	v_cvt_pk_bf16_f32 v58, v140, v141
	v_cvt_pk_bf16_f32 v59, v136, v137
	v_lshl_add_u64 v[60:61], v[182:183], 1, v[60:61]
	global_store_dwordx4 v[60:61], v[56:59], off
; __device__ __forceinline__ unsigned cvt_pk_bf16(float lo, float hi) { return pk2(lo, hi); }
; __device__ __forceinline__ f32x4 bf4lo(u32x4 g) { return (f32x4){__builtin_bit_cast(float, g.x << 16), __builtin_bit_cast(float, g.x & 0xffff0000u), __builtin_bit_cast(float, g.y << 16), __builtin_bit_cast(float, g.y & 0xffff0000u)}; }
; __device__ __forceinline__ f32x4 bf4hi(u32x4 g) { return (f32x4){__builtin_bit_cast(float, g.z << 16), __builtin_bit_cast(float, g.z & 0xffff0000u), __builtin_bit_cast(float, g.w << 16), __builtin_bit_cast(float, g.w & 0xffff0000u)}; }
;     __device__ __forceinline__ void operator()(const f32x4 (&acc)[2][1][4][2], f32x4 (&mr)[2][4][2], const Unit& u, int wr, int wc, int fr, int fq) const {
;     ...
;         for (int ai = 0; ai < 2; ++ai)
; #pragma unroll
;             for (int m = 0; m < 4; ++m) {
;                 const f32x4 p0 = acc[ai][0][m][0] * bf4lo(gv[ai][m]), p1 = acc[ai][0][m][1] * bf4hi(gv[ai][m]);
;                 if (u.pb == 0) { mr[ai][m][0] = p0; mr[ai][m][1] = p1; } else { mr[ai][m][0] += p0; mr[ai][m][1] += p1; }
;                 if (u.pb == 3) { const f32x4 v0 = mr[ai][m][0], v1 = mr[ai][m][1];
;                     u32x4 w; w.x = cvt_pk_bf16(v0[0], v0[1]); w.y = cvt_pk_bf16(v0[2], v0[3]); w.z = cvt_pk_bf16(v1[0], v1[1]); w.w = cvt_pk_bf16(v1[2], v1[3]);
;                     *(u32x4*)(MB + (size_t)(row0 + ai * HALF + m * 16) * D + col0) = w; } }
.LBB0_1381:
	s_waitcnt vmcnt(4)
	s_nop 1
	v_lshlrev_b32_e32 v56, 16, v72
	v_and_b32_e32 v57, 0xffff0000, v72
	v_lshlrev_b32_e32 v58, 16, v73
	v_and_b32_e32 v59, 0xffff0000, v73
	v_lshlrev_b32_e32 v68, 16, v74
	v_and_b32_e32 v69, 0xffff0000, v74
	v_lshlrev_b32_e32 v70, 16, v75
	v_and_b32_e32 v71, 0xffff0000, v75
	v_pk_mul_f32 v[60:61], v[48:49], v[56:57]
	v_pk_mul_f32 v[62:63], v[50:51], v[58:59]
	v_pk_mul_f32 v[72:73], v[44:45], v[68:69]
	v_pk_mul_f32 v[74:75], v[46:47], v[70:71]
	v_pk_fma_f32 v[48:49], v[48:49], v[56:57], v[146:147]
	v_pk_fma_f32 v[50:51], v[50:51], v[58:59], v[142:143]
	v_pk_fma_f32 v[44:45], v[44:45], v[68:69], v[132:133]
	v_pk_fma_f32 v[46:47], v[46:47], v[70:71], v[128:129]
	v_cndmask_b32_e64 v133, v45, v73, s[38:39]
	v_cndmask_b32_e64 v129, v47, v75, s[38:39]
	v_cndmask_b32_e64 v128, v46, v74, s[38:39]
	v_cndmask_b32_e64 v132, v44, v72, s[38:39]
	v_cndmask_b32_e64 v143, v51, v63, s[38:39]
	v_cndmask_b32_e64 v142, v50, v62, s[38:39]
	v_cndmask_b32_e64 v147, v49, v61, s[38:39]
	s_and_b64 vcc, exec, s[42:43]
	v_cndmask_b32_e64 v146, v48, v60, s[38:39]
	s_cbranch_vccnz .LBB0_1383
	v_lshlrev_b64 v[48:49], 12, v[192:193]
	v_lshl_add_u64 v[48:49], s[8:9], 0, v[48:49]
	v_cvt_pk_bf16_f32 v44, v146, v147
	v_cvt_pk_bf16_f32 v45, v142, v143
	v_cvt_pk_bf16_f32 v46, v132, v133
	v_cvt_pk_bf16_f32 v47, v128, v129
	v_lshl_add_u64 v[48:49], v[182:183], 1, v[48:49]
	global_store_dwordx4 v[48:49], v[44:47], off
.LBB0_1383:
	s_waitcnt vmcnt(3)
	s_nop 1
	v_lshlrev_b32_e32 v44, 16, v64
	v_and_b32_e32 v45, 0xffff0000, v64
	v_lshlrev_b32_e32 v46, 16, v65
	v_and_b32_e32 v47, 0xffff0000, v65
	v_lshlrev_b32_e32 v56, 16, v66
	v_and_b32_e32 v57, 0xffff0000, v66
	v_lshlrev_b32_e32 v58, 16, v67
	v_and_b32_e32 v59, 0xffff0000, v67
	v_pk_mul_f32 v[48:49], v[40:41], v[44:45]
	v_pk_mul_f32 v[50:51], v[42:43], v[46:47]
	v_pk_mul_f32 v[60:61], v[36:37], v[56:57]
	v_pk_mul_f32 v[62:63], v[38:39], v[58:59]
	v_pk_fma_f32 v[40:41], v[40:41], v[44:45], v[138:139]
	v_pk_fma_f32 v[42:43], v[42:43], v[46:47], v[134:135]
	v_pk_fma_f32 v[36:37], v[36:37], v[56:57], v[124:125]
	v_pk_fma_f32 v[38:39], v[38:39], v[58:59], v[120:121]
	v_cndmask_b32_e64 v125, v37, v61, s[38:39]
	v_cndmask_b32_e64 v121, v39, v63, s[38:39]
	v_cndmask_b32_e64 v120, v38, v62, s[38:39]
	v_cndmask_b32_e64 v124, v36, v60, s[38:39]
	v_cndmask_b32_e64 v135, v43, v51, s[38:39]
	v_cndmask_b32_e64 v134, v42, v50, s[38:39]
	v_cndmask_b32_e64 v139, v41, v49, s[38:39]
	s_and_b64 vcc, exec, s[42:43]
	v_cndmask_b32_e64 v138, v40, v48, s[38:39]
	s_cbranch_vccnz .LBB0_1385
	v_lshlrev_b64 v[40:41], 12, v[190:191]
	v_lshl_add_u64 v[40:41], s[8:9], 0, v[40:41]
	v_cvt_pk_bf16_f32 v36, v138, v139
	v_cvt_pk_bf16_f32 v37, v134, v135
	v_cvt_pk_bf16_f32 v38, v124, v125
	v_cvt_pk_bf16_f32 v39, v120, v121
	v_lshl_add_u64 v[40:41], v[182:183], 1, v[40:41]
	global_store_dwordx4 v[40:41], v[36:39], off
; __device__ __forceinline__ unsigned cvt_pk_bf16(float lo, float hi) { return pk2(lo, hi); }
; __device__ __forceinline__ f32x4 bf4lo(u32x4 g) { return (f32x4){__builtin_bit_cast(float, g.x << 16), __builtin_bit_cast(float, g.x & 0xffff0000u), __builtin_bit_cast(float, g.y << 16), __builtin_bit_cast(float, g.y & 0xffff0000u)}; }
; __device__ __forceinline__ f32x4 bf4hi(u32x4 g) { return (f32x4){__builtin_bit_cast(float, g.z << 16), __builtin_bit_cast(float, g.z & 0xffff0000u), __builtin_bit_cast(float, g.w << 16), __builtin_bit_cast(float, g.w & 0xffff0000u)}; }
;     __device__ __forceinline__ void operator()(const f32x4 (&acc)[2][1][4][2], f32x4 (&mr)[2][4][2], const Unit& u, int wr, int wc, int fr, int fq) const {
;     ...
;         for (int ai = 0; ai < 2; ++ai)
; #pragma unroll
;             for (int m = 0; m < 4; ++m) {
;                 const f32x4 p0 = acc[ai][0][m][0] * bf4lo(gv[ai][m]), p1 = acc[ai][0][m][1] * bf4hi(gv[ai][m]);
;                 if (u.pb == 0) { mr[ai][m][0] = p0; mr[ai][m][1] = p1; } else { mr[ai][m][0] += p0; mr[ai][m][1] += p1; }
;                 if (u.pb == 3) { const f32x4 v0 = mr[ai][m][0], v1 = mr[ai][m][1];
;                     u32x4 w; w.x = cvt_pk_bf16(v0[0], v0[1]); w.y = cvt_pk_bf16(v0[2], v0[3]); w.z = cvt_pk_bf16(v1[0], v1[1]); w.w = cvt_pk_bf16(v1[2], v1[3]);
;                     *(u32x4*)(MB + (size_t)(row0 + ai * HALF + m * 16) * D + col0) = w; } }
.LBB0_1385:
	s_waitcnt vmcnt(2)
	s_nop 1
	v_lshlrev_b32_e32 v36, 16, v52
	v_and_b32_e32 v37, 0xffff0000, v52
	v_lshlrev_b32_e32 v38, 16, v53
	v_and_b32_e32 v39, 0xffff0000, v53
	v_lshlrev_b32_e32 v44, 16, v54
	v_and_b32_e32 v45, 0xffff0000, v54
	v_lshlrev_b32_e32 v46, 16, v55
	v_and_b32_e32 v47, 0xffff0000, v55
	v_pk_mul_f32 v[40:41], v[26:27], v[36:37]
	v_pk_mul_f32 v[42:43], v[28:29], v[38:39]
	v_pk_mul_f32 v[48:49], v[22:23], v[44:45]
	v_pk_mul_f32 v[50:51], v[24:25], v[46:47]
	v_pk_fma_f32 v[26:27], v[26:27], v[36:37], v[130:131]
	v_pk_fma_f32 v[28:29], v[28:29], v[38:39], v[126:127]
	v_pk_fma_f32 v[22:23], v[22:23], v[44:45], v[116:117]
	v_pk_fma_f32 v[24:25], v[24:25], v[46:47], v[112:113]
	v_cndmask_b32_e64 v117, v23, v49, s[38:39]
	v_cndmask_b32_e64 v113, v25, v51, s[38:39]
	v_cndmask_b32_e64 v112, v24, v50, s[38:39]
	v_cndmask_b32_e64 v116, v22, v48, s[38:39]
	v_cndmask_b32_e64 v127, v29, v43, s[38:39]
	v_cndmask_b32_e64 v126, v28, v42, s[38:39]
	v_cndmask_b32_e64 v131, v27, v41, s[38:39]
	s_and_b64 vcc, exec, s[42:43]
	v_cndmask_b32_e64 v130, v26, v40, s[38:39]
	s_cbranch_vccnz .LBB0_1387
	v_lshlrev_b64 v[26:27], 12, v[188:189]
	v_lshl_add_u64 v[26:27], s[8:9], 0, v[26:27]
	v_cvt_pk_bf16_f32 v22, v130, v131
	v_cvt_pk_bf16_f32 v23, v126, v127
	v_cvt_pk_bf16_f32 v24, v116, v117
	v_cvt_pk_bf16_f32 v25, v112, v113
	v_lshl_add_u64 v[26:27], v[182:183], 1, v[26:27]
	global_store_dwordx4 v[26:27], v[22:25], off
.LBB0_1387:
	s_waitcnt vmcnt(1)
	s_nop 1
	v_lshlrev_b32_e32 v22, 16, v30
	v_and_b32_e32 v23, 0xffff0000, v30
	v_lshlrev_b32_e32 v24, 16, v31
	v_and_b32_e32 v25, 0xffff0000, v31
	v_lshlrev_b32_e32 v30, 16, v32
	v_and_b32_e32 v31, 0xffff0000, v32
	v_lshlrev_b32_e32 v32, 16, v33
	v_and_b32_e32 v33, 0xffff0000, v33
	v_pk_mul_f32 v[26:27], v[14:15], v[22:23]
	v_pk_mul_f32 v[28:29], v[16:17], v[24:25]
	v_pk_mul_f32 v[36:37], v[10:11], v[30:31]
	v_pk_mul_f32 v[38:39], v[12:13], v[32:33]
	v_pk_fma_f32 v[14:15], v[14:15], v[22:23], v[122:123]
	v_pk_fma_f32 v[16:17], v[16:17], v[24:25], v[118:119]
	v_pk_fma_f32 v[10:11], v[10:11], v[30:31], v[108:109]
	v_pk_fma_f32 v[12:13], v[12:13], v[32:33], v[106:107]
	v_cndmask_b32_e64 v109, v11, v37, s[38:39]
	v_cndmask_b32_e64 v107, v13, v39, s[38:39]
	v_cndmask_b32_e64 v106, v12, v38, s[38:39]
	v_cndmask_b32_e64 v108, v10, v36, s[38:39]
	v_cndmask_b32_e64 v119, v17, v29, s[38:39]
	v_cndmask_b32_e64 v118, v16, v28, s[38:39]
	v_cndmask_b32_e64 v123, v15, v27, s[38:39]
	s_and_b64 vcc, exec, s[42:43]
	v_cndmask_b32_e64 v122, v14, v26, s[38:39]
	s_cbranch_vccnz .LBB0_1389
	v_lshlrev_b64 v[14:15], 12, v[186:187]
	v_lshl_add_u64 v[14:15], s[8:9], 0, v[14:15]
	v_cvt_pk_bf16_f32 v10, v122, v123
	v_cvt_pk_bf16_f32 v11, v118, v119
	v_cvt_pk_bf16_f32 v12, v108, v109
	v_cvt_pk_bf16_f32 v13, v106, v107
	v_lshl_add_u64 v[14:15], v[182:183], 1, v[14:15]
	global_store_dwordx4 v[14:15], v[10:13], off
.LBB0_1389:
	s_waitcnt vmcnt(0)
	s_nop 1
	v_lshlrev_b32_e32 v10, 16, v18
	v_and_b32_e32 v11, 0xffff0000, v18
	v_lshlrev_b32_e32 v12, 16, v19
	v_and_b32_e32 v13, 0xffff0000, v19
	v_lshlrev_b32_e32 v18, 16, v20
	v_and_b32_e32 v19, 0xffff0000, v20
	v_lshlrev_b32_e32 v20, 16, v21
	v_and_b32_e32 v21, 0xffff0000, v21
	v_pk_mul_f32 v[14:15], v[6:7], v[10:11]
	v_pk_mul_f32 v[16:17], v[8:9], v[12:13]
	v_pk_mul_f32 v[22:23], v[2:3], v[18:19]
	v_pk_mul_f32 v[24:25], v[4:5], v[20:21]
	v_pk_fma_f32 v[6:7], v[6:7], v[10:11], v[114:115]
	v_pk_fma_f32 v[8:9], v[8:9], v[12:13], v[110:111]
	v_pk_fma_f32 v[2:3], v[2:3], v[18:19], v[104:105]
	v_pk_fma_f32 v[4:5], v[4:5], v[20:21], v[102:103]
	v_cndmask_b32_e64 v105, v3, v23, s[38:39]
	v_cndmask_b32_e64 v103, v5, v25, s[38:39]
	v_cndmask_b32_e64 v102, v4, v24, s[38:39]
	v_cndmask_b32_e64 v104, v2, v22, s[38:39]
	v_cndmask_b32_e64 v111, v9, v17, s[38:39]
	v_cndmask_b32_e64 v110, v8, v16, s[38:39]
	v_cndmask_b32_e64 v115, v7, v15, s[38:39]
	s_and_b64 vcc, exec, s[42:43]
	v_cndmask_b32_e64 v114, v6, v14, s[38:39]
	s_cbranch_vccnz .LBB0_1391
	v_lshlrev_b64 v[6:7], 12, v[184:185]
	v_lshl_add_u64 v[6:7], s[8:9], 0, v[6:7]
	v_cvt_pk_bf16_f32 v2, v114, v115
	v_cvt_pk_bf16_f32 v3, v110, v111
	v_cvt_pk_bf16_f32 v4, v104, v105
	v_cvt_pk_bf16_f32 v5, v102, v103
	v_lshl_add_u64 v[6:7], v[182:183], 1, v[6:7]
	global_store_dwordx4 v[6:7], v[2:5], off

;     __device__ __forceinline__ void operator()(const f32x4 (&acc)[2][2][4][2], const Unit& u, int wr, int wc, int fr, int fq) const {
;     ...
;         for (int aih = 0; aih < 4; ++aih) { const int ai = aih >> 1, m0 = (aih & 1) * 2;
;             f32x4 rv[4][2][2];
;             if (rb16) {
;                 u32x4 rw[2][2];
; #pragma unroll
;                 for (int m = m0; m < m0 + 2; ++m)
; #pragma unroll
;                     for (int bj = 0; bj < 2; ++bj) rw[m - m0][bj] = *(const u32x4*)((const bf16_t*)r0 + (size_t)(row0 + ai * HALF + m * 16) * D + col0 + bj * HALF);
; #pragma unroll
;                 for (int m = m0; m < m0 + 2; ++m)
; #pragma unroll
;                     for (int bj = 0; bj < 2; ++bj) { const u32x4 x = rw[m - m0][bj];
;                         rv[m][bj][0] = (f32x4){__builtin_bit_cast(float, x.x << 16), __builtin_bit_cast(float, x.x & 0xffff0000u), __builtin_bit_cast(float, x.y << 16), __builtin_bit_cast(float, x.y & 0xffff0000u)};
;                         rv[m][bj][1] = (f32x4){__builtin_bit_cast(float, x.z << 16), __builtin_bit_cast(float, x.z & 0xffff0000u), __builtin_bit_cast(float, x.w << 16), __builtin_bit_cast(float, x.w & 0xffff0000u)}; }
.LBB0_1492:
	v_or_b32_e32 v138, 32, v194
	v_ashrrev_i32_e32 v139, 31, v138
	v_cndmask_b32_e64 v100, 0, 1, s[10:11]
	v_cmp_ne_u32_e64 s[46:47], 1, v100
	s_andn2_b64 vcc, exec, s[10:11]
	v_lshlrev_b64 v[136:137], 12, v[138:139]
	v_or_b32_e32 v132, 48, v194
	s_cbranch_vccnz .LBB0_1522
	v_ashrrev_i32_e32 v133, 31, v132
	v_lshlrev_b64 v[134:135], 12, v[138:139]
	v_lshlrev_b64 v[108:109], 12, v[132:133]
	v_lshl_add_u64 v[104:105], v[200:201], 0, v[134:135]
	v_lshl_add_u64 v[108:109], v[200:201], 0, v[108:109]
	s_waitcnt lgkmcnt(0)
	global_load_dwordx4 v[100:103], v[104:105], off
	s_nop 0
	global_load_dwordx4 v[104:107], v[104:105], off offset:256
	s_nop 0
	global_load_dwordx4 v[112:115], v[108:109], off
	global_load_dwordx4 v[140:143], v[108:109], off offset:256
	s_waitcnt vmcnt(3)
	v_lshlrev_b32_e32 v120, 16, v100
	v_and_b32_e32 v121, 0xffff0000, v100
	v_lshlrev_b32_e32 v122, 16, v101
	v_and_b32_e32 v123, 0xffff0000, v101
	v_lshlrev_b32_e32 v128, 16, v102
	v_and_b32_e32 v129, 0xffff0000, v102
	v_lshlrev_b32_e32 v130, 16, v103
	v_and_b32_e32 v131, 0xffff0000, v103
	s_waitcnt vmcnt(2)
	v_lshlrev_b32_e32 v116, 16, v104
	v_and_b32_e32 v117, 0xffff0000, v104
	v_lshlrev_b32_e32 v118, 16, v105
	v_and_b32_e32 v119, 0xffff0000, v105
	v_lshlrev_b32_e32 v124, 16, v106
	v_and_b32_e32 v125, 0xffff0000, v106
	v_lshlrev_b32_e32 v126, 16, v107
	v_and_b32_e32 v127, 0xffff0000, v107
	s_waitcnt vmcnt(1)
	v_lshlrev_b32_e32 v108, 16, v112
	v_and_b32_e32 v109, 0xffff0000, v112
	v_lshlrev_b32_e32 v110, 16, v113
	v_and_b32_e32 v111, 0xffff0000, v113
	v_lshlrev_b32_e32 v112, 16, v114
	v_and_b32_e32 v113, 0xffff0000, v114
	v_lshlrev_b32_e32 v114, 16, v115
	v_and_b32_e32 v115, 0xffff0000, v115
	s_waitcnt vmcnt(0)
	v_lshlrev_b32_e32 v100, 16, v140
	v_and_b32_e32 v101, 0xffff0000, v140
	v_lshlrev_b32_e32 v102, 16, v141
	v_and_b32_e32 v103, 0xffff0000, v141
	v_lshlrev_b32_e32 v104, 16, v142
	v_and_b32_e32 v105, 0xffff0000, v142
	v_lshlrev_b32_e32 v106, 16, v143
	v_and_b32_e32 v107, 0xffff0000, v143
	s_cbranch_execnz .LBB0_1495

;     __device__ __forceinline__ void operator()(const f32x4 (&acc)[2][2][4][2], const Unit& u, int wr, int wc, int fr, int fq) const {
;     ...
;         for (int aih = 0; aih < 4; ++aih) { const int ai = aih >> 1, m0 = (aih & 1) * 2;
;             f32x4 rv[4][2][2];
;             if (rb16) {
;                 u32x4 rw[2][2];
; #pragma unroll
;                 for (int m = m0; m < m0 + 2; ++m)
; #pragma unroll
;                     for (int bj = 0; bj < 2; ++bj) rw[m - m0][bj] = *(const u32x4*)((const bf16_t*)r0 + (size_t)(row0 + ai * HALF + m * 16) * D + col0 + bj * HALF);
; #pragma unroll
;                 for (int m = m0; m < m0 + 2; ++m)
; #pragma unroll
;                     for (int bj = 0; bj < 2; ++bj) { const u32x4 x = rw[m - m0][bj];
;                         rv[m][bj][0] = (f32x4){__builtin_bit_cast(float, x.x << 16), __builtin_bit_cast(float, x.x & 0xffff0000u), __builtin_bit_cast(float, x.y << 16), __builtin_bit_cast(float, x.y & 0xffff0000u)};
;                         rv[m][bj][1] = (f32x4){__builtin_bit_cast(float, x.z << 16), __builtin_bit_cast(float, x.z & 0xffff0000u), __builtin_bit_cast(float, x.w << 16), __builtin_bit_cast(float, x.w & 0xffff0000u)}; }
.LBB0_1501:
	v_add_u32_e32 v104, 0x80, v194
	v_ashrrev_i32_e32 v105, 31, v104
	s_and_b64 vcc, exec, s[46:47]
	v_lshlrev_b64 v[102:103], 12, v[104:105]
	s_cbranch_vccnz .LBB0_1523
	v_lshl_add_u64 v[80:81], v[200:201], 0, v[192:193]
	s_waitcnt lgkmcnt(0)
	v_lshlrev_b64 v[100:101], 12, v[104:105]
	v_add_co_u32_e32 v76, vcc, 0x90000, v80
	s_mov_b64 s[2:3], 0x90000
	v_lshl_add_u64 v[72:73], v[200:201], 0, v[100:101]
	v_addc_co_u32_e32 v77, vcc, 0, v81, vcc
	v_lshl_add_u64 v[80:81], v[80:81], 0, s[2:3]
	global_load_dwordx4 v[68:71], v[72:73], off
	s_nop 0
	global_load_dwordx4 v[72:75], v[72:73], off offset:256
	s_nop 0
	global_load_dwordx4 v[76:79], v[76:77], off
	s_waitcnt vmcnt(2)
	v_lshlrev_b32_e32 v88, 16, v68
	global_load_dwordx4 v[106:109], v[80:81], off offset:256
	v_and_b32_e32 v89, 0xffff0000, v68
	v_lshlrev_b32_e32 v90, 16, v69
	v_and_b32_e32 v91, 0xffff0000, v69
	v_lshlrev_b32_e32 v96, 16, v70
	v_and_b32_e32 v97, 0xffff0000, v70
	v_lshlrev_b32_e32 v98, 16, v71
	v_and_b32_e32 v99, 0xffff0000, v71
	s_waitcnt vmcnt(2)
	v_lshlrev_b32_e32 v84, 16, v72
	v_and_b32_e32 v85, 0xffff0000, v72
	v_lshlrev_b32_e32 v86, 16, v73
	v_and_b32_e32 v87, 0xffff0000, v73
	v_lshlrev_b32_e32 v92, 16, v74
	v_and_b32_e32 v93, 0xffff0000, v74
	v_lshlrev_b32_e32 v94, 16, v75
	v_and_b32_e32 v95, 0xffff0000, v75
	s_waitcnt vmcnt(1)
	v_lshlrev_b32_e32 v68, 16, v76
	v_and_b32_e32 v69, 0xffff0000, v76
	v_lshlrev_b32_e32 v70, 16, v77
	v_and_b32_e32 v71, 0xffff0000, v77
	v_lshlrev_b32_e32 v80, 16, v78
	v_and_b32_e32 v81, 0xffff0000, v78
	v_lshlrev_b32_e32 v82, 16, v79
	v_and_b32_e32 v83, 0xffff0000, v79
	s_waitcnt vmcnt(0)
	v_lshlrev_b32_e32 v72, 16, v106
	v_and_b32_e32 v73, 0xffff0000, v106
	v_lshlrev_b32_e32 v74, 16, v107
	v_and_b32_e32 v75, 0xffff0000, v107
	v_lshlrev_b32_e32 v76, 16, v108
	v_and_b32_e32 v77, 0xffff0000, v108
	v_lshlrev_b32_e32 v78, 16, v109
	v_and_b32_e32 v79, 0xffff0000, v109
	s_cbranch_execnz .LBB0_1504

;     __device__ __forceinline__ void operator()(const f32x4 (&acc)[2][2][4][2], const Unit& u, int wr, int wc, int fr, int fq) const {
;     ...
;         for (int aih = 0; aih < 4; ++aih) { const int ai = aih >> 1, m0 = (aih & 1) * 2;
;             f32x4 rv[4][2][2];
;             if (rb16) {
;                 u32x4 rw[2][2];
; #pragma unroll
;                 for (int m = m0; m < m0 + 2; ++m)
; #pragma unroll
;                     for (int bj = 0; bj < 2; ++bj) rw[m - m0][bj] = *(const u32x4*)((const bf16_t*)r0 + (size_t)(row0 + ai * HALF + m * 16) * D + col0 + bj * HALF);
; #pragma unroll
;                 for (int m = m0; m < m0 + 2; ++m)
; #pragma unroll
;                     for (int bj = 0; bj < 2; ++bj) { const u32x4 x = rw[m - m0][bj];
;                         rv[m][bj][0] = (f32x4){__builtin_bit_cast(float, x.x << 16), __builtin_bit_cast(float, x.x & 0xffff0000u), __builtin_bit_cast(float, x.y << 16), __builtin_bit_cast(float, x.y & 0xffff0000u)};
;                         rv[m][bj][1] = (f32x4){__builtin_bit_cast(float, x.z << 16), __builtin_bit_cast(float, x.z & 0xffff0000u), __builtin_bit_cast(float, x.w << 16), __builtin_bit_cast(float, x.w & 0xffff0000u)}; }
.LBB0_1510:
	v_add_u32_e32 v72, 0xa0, v194
	v_ashrrev_i32_e32 v73, 31, v72
	s_and_b64 vcc, exec, s[46:47]
	s_waitcnt lgkmcnt(0)
	v_lshlrev_b64 v[68:69], 12, v[72:73]
	s_cbranch_vccnz .LBB0_1524
	v_lshl_add_u64 v[48:49], v[200:201], 0, v[192:193]
	v_lshlrev_b64 v[70:71], 12, v[72:73]
	v_add_co_u32_e32 v44, vcc, 0xb0000, v48
	s_mov_b64 s[2:3], 0xb0000
	v_lshl_add_u64 v[40:41], v[200:201], 0, v[70:71]
	v_addc_co_u32_e32 v45, vcc, 0, v49, vcc
	v_lshl_add_u64 v[48:49], v[48:49], 0, s[2:3]
	global_load_dwordx4 v[36:39], v[40:41], off
	s_nop 0
	global_load_dwordx4 v[40:43], v[40:41], off offset:256
	s_nop 0
	global_load_dwordx4 v[44:47], v[44:45], off
	s_waitcnt vmcnt(2)
	v_lshlrev_b32_e32 v56, 16, v36
	global_load_dwordx4 v[74:77], v[48:49], off offset:256
	v_and_b32_e32 v57, 0xffff0000, v36
	v_lshlrev_b32_e32 v58, 16, v37
	v_and_b32_e32 v59, 0xffff0000, v37
	v_lshlrev_b32_e32 v64, 16, v38
	v_and_b32_e32 v65, 0xffff0000, v38
	v_lshlrev_b32_e32 v66, 16, v39
	v_and_b32_e32 v67, 0xffff0000, v39
	s_waitcnt vmcnt(2)
	v_lshlrev_b32_e32 v52, 16, v40
	v_and_b32_e32 v53, 0xffff0000, v40
	v_lshlrev_b32_e32 v54, 16, v41
	v_and_b32_e32 v55, 0xffff0000, v41
	v_lshlrev_b32_e32 v60, 16, v42
	v_and_b32_e32 v61, 0xffff0000, v42
	v_lshlrev_b32_e32 v62, 16, v43
	v_and_b32_e32 v63, 0xffff0000, v43
	s_waitcnt vmcnt(1)
	v_lshlrev_b32_e32 v36, 16, v44
	v_and_b32_e32 v37, 0xffff0000, v44
	v_lshlrev_b32_e32 v38, 16, v45
	v_and_b32_e32 v39, 0xffff0000, v45
	v_lshlrev_b32_e32 v48, 16, v46
	v_and_b32_e32 v49, 0xffff0000, v46
	v_lshlrev_b32_e32 v50, 16, v47
	v_and_b32_e32 v51, 0xffff0000, v47
	s_waitcnt vmcnt(0)
	v_lshlrev_b32_e32 v40, 16, v74
	v_and_b32_e32 v41, 0xffff0000, v74
	v_lshlrev_b32_e32 v42, 16, v75
	v_and_b32_e32 v43, 0xffff0000, v75
	v_lshlrev_b32_e32 v44, 16, v76
	v_and_b32_e32 v45, 0xffff0000, v76
	v_lshlrev_b32_e32 v46, 16, v77
	v_and_b32_e32 v47, 0xffff0000, v77
	s_cbranch_execnz .LBB0_1513

;     __device__ __forceinline__ void operator()(const f32x4 (&acc)[2][2][4][2], const Unit& u, int wr, int wc, int fr, int fq) const {
;     ...
;         for (int aih = 0; aih < 4; ++aih) { const int ai = aih >> 1, m0 = (aih & 1) * 2;
;             f32x4 rv[4][2][2];
;             if (rb16) {
;                 u32x4 rw[2][2];
; #pragma unroll
;                 for (int m = m0; m < m0 + 2; ++m)
; #pragma unroll
;                     for (int bj = 0; bj < 2; ++bj) rw[m - m0][bj] = *(const u32x4*)((const bf16_t*)r0 + (size_t)(row0 + ai * HALF + m * 16) * D + col0 + bj * HALF);
; #pragma unroll
;                 for (int m = m0; m < m0 + 2; ++m)
; #pragma unroll
;                     for (int bj = 0; bj < 2; ++bj) { const u32x4 x = rw[m - m0][bj];
;                         rv[m][bj][0] = (f32x4){__builtin_bit_cast(float, x.x << 16), __builtin_bit_cast(float, x.x & 0xffff0000u), __builtin_bit_cast(float, x.y << 16), __builtin_bit_cast(float, x.y & 0xffff0000u)};
;                         rv[m][bj][1] = (f32x4){__builtin_bit_cast(float, x.z << 16), __builtin_bit_cast(float, x.z & 0xffff0000u), __builtin_bit_cast(float, x.w << 16), __builtin_bit_cast(float, x.w & 0xffff0000u)}; }
.Lepi_skip_1492:
	s_waitcnt vmcnt(0)
	s_branch .LBB0_1492
